# baseline (speedup 1.0000x reference)
; #define SBAR() __builtin_amdgcn_sched_barrier(0)
; #define SLOAD(i, t) do { const long rb_ = TROW(t); const char* vt_ = (const char*)Vh + rb_ * (LDK * 2); const char* kt_ = (const char*)Kh + rb_ * (LDK * 2); \
;     sr_[i].vs0 = *(const bf16x8*)(vt_ + lo0); sr_[i].vs1 = *(const bf16x8*)(vt_ + lo0 + 32 * LDK * 2); \
;     sr_[i].ks0 = *(const bf16x8*)(kt_ + lo0); sr_[i].ks1 = *(const bf16x8*)(kt_ + lo0 + 32 * LDK * 2); } while (0)
; __device__ __forceinline__ void finishSM(f32x16& p0, f32x16& p1, float alpha, float& l_reg, bf16x8& pa0, bf16x8& pa1, bf16x8& pa2, bf16x8& pa3) {
; #pragma unroll
;   for (int r = 0; r < 16; ++r) p1[r] = __builtin_amdgcn_exp2f(p1[r]);
;   float ps = 0;
; #pragma unroll
;   for (int r = 0; r < 16; ++r) ps += p0[r];
; #pragma unroll
;   for (int r = 0; r < 16; ++r) ps += p1[r];
;   { auto rr = __builtin_amdgcn_permlane32_swap(__float_as_uint(ps), __float_as_uint(ps), false, false);
;     ps = __uint_as_float(rr[0]) + __uint_as_float(rr[1]); }
;   l_reg = l_reg * alpha + ps;
;     ...
;   PK4(p0, 0, pa0); PK4(p0, 8, pa1); PK4(p1, 0, pa2); PK4(p1, 8, pa3);
;     ...
; }
; __device__ __forceinline__ void qkt(f32x16& p0, f32x16& p1, const bf16_t* Ks, const bf16x8* qr, int r32, int hi) {
;   p0 = f32x16{}; p1 = f32x16{};
; #pragma unroll
;   for (int d0 = 0; d0 < 8; ++d0) { int cb = (d0 * 16 + hi * 8) * 2;
;     bf16x8 b0 = *reinterpret_cast<const bf16x8*>((const char*)Ks + KSWZ(r32, cb));
;     bf16x8 b1 = *reinterpret_cast<const bf16x8*>((const char*)Ks + KSWZ(32 + r32, cb));
;     p0 = __builtin_amdgcn_mfma_f32_32x32x16_bf16(b0, qr[d0], p0, 0, 0, 0);
;     p1 = __builtin_amdgcn_mfma_f32_32x32x16_bf16(b1, qr[d0], p1, 0, 0, 0); }
; }
; template <bool META>
; __device__ __forceinline__ void attn_unit(const bf16_t* Q, bf16_t* Oo, const bf16_t* __restrict__ Kb, const bf16_t* __restrict__ Vb, int b, int kvh, int h, int qb, char* lds, const int tid, const float* qn, const float* RT) {
;     ...
;   for (int j = 1; j + 1 < NT; j += 2) {
;     const int bn = bc == 2 ? 0 : bc + 1, bp = bc == 0 ? 2 : bc - 1;
;     SBAR(); qkt(pB0, pB1, (bf16_t*)((char*)K_lds + bc * SHM_K), qr, r32, hi);
;     finishSM(pA0, pA1, alA, l_reg, pa0, pa1, pa2, pa3); SBAR();
;     SLOAD(SO, j + 1);
.LBB0_260:
	s_mov_b32 s6, s28
	s_sub_u32 s0, s6, 1
	s_cselect_b32 s28, 2, s0
	s_lshl_b32 s9, s6, 14
	s_add_i32 s0, s9, 0
	v_add_u32_e32 v195, s0, v182
	ds_read_b128 v[66:69], v195 offset:49152
	ds_read_b128 v[70:73], v195 offset:50176
	ds_read_b128 v[210:213], v195 offset:51200
	ds_read_b128 v[214:217], v195 offset:52224
	s_waitcnt lgkmcnt(3)
	s_setprio 1
	v_mfma_f32_32x32x16_bf16 v[82:97], v[66:69], v[98:101], 0
	v_exp_f32_e32 v144, v144
	v_exp_f32_e32 v145, v145
	v_exp_f32_e32 v142, v142
	v_exp_f32_e32 v143, v143
	v_exp_f32_e32 v140, v140
	v_exp_f32_e32 v141, v141
	v_exp_f32_e32 v138, v138
	s_waitcnt lgkmcnt(2)
	v_mfma_f32_32x32x16_bf16 v[66:81], v[70:73], v[98:101], 0
	v_exp_f32_e32 v139, v139
	v_exp_f32_e32 v136, v136
	v_exp_f32_e32 v137, v137
	v_exp_f32_e32 v134, v134
	v_exp_f32_e32 v135, v135
	v_exp_f32_e32 v132, v132
	v_exp_f32_e32 v133, v133
	s_waitcnt lgkmcnt(1)
	v_mfma_f32_32x32x16_bf16 v[82:97], v[210:213], v[102:105], v[82:97]
	v_exp_f32_e32 v130, v130
	v_exp_f32_e32 v131, v131
	s_waitcnt lgkmcnt(0)
	v_mfma_f32_32x32x16_bf16 v[66:81], v[214:217], v[102:105], v[66:81]
	ds_read_b128 v[210:213], v195 offset:53248
	ds_read_b128 v[214:217], v195 offset:54272
	s_waitcnt lgkmcnt(1)
	v_mfma_f32_32x32x16_bf16 v[82:97], v[210:213], v[106:109], v[82:97]
	s_waitcnt lgkmcnt(0)
	v_mfma_f32_32x32x16_bf16 v[66:81], v[214:217], v[106:109], v[66:81]
	ds_read_b128 v[210:213], v195 offset:55296
	ds_read_b128 v[214:217], v195 offset:56320
	s_waitcnt lgkmcnt(1)
	v_mfma_f32_32x32x16_bf16 v[82:97], v[210:213], v[110:113], v[82:97]
	s_waitcnt lgkmcnt(0)
	v_mfma_f32_32x32x16_bf16 v[66:81], v[214:217], v[110:113], v[66:81]
	ds_read_b128 v[210:213], v195 offset:57344
	ds_read_b128 v[214:217], v195 offset:58368
	s_waitcnt lgkmcnt(1)
	v_mfma_f32_32x32x16_bf16 v[82:97], v[210:213], v[114:117], v[82:97]
	s_waitcnt lgkmcnt(0)
	v_mfma_f32_32x32x16_bf16 v[66:81], v[214:217], v[114:117], v[66:81]
	ds_read_b128 v[210:213], v195 offset:59392
	ds_read_b128 v[214:217], v195 offset:60416
	s_waitcnt lgkmcnt(1)
	v_mfma_f32_32x32x16_bf16 v[82:97], v[210:213], v[118:121], v[82:97]
	s_waitcnt lgkmcnt(0)
	v_mfma_f32_32x32x16_bf16 v[66:81], v[214:217], v[118:121], v[66:81]
	ds_read_b128 v[210:213], v195 offset:61440
	ds_read_b128 v[214:217], v195 offset:62464
	s_waitcnt lgkmcnt(1)
	v_mfma_f32_32x32x16_bf16 v[82:97], v[210:213], v[122:125], v[82:97]
	s_waitcnt lgkmcnt(0)
	v_mfma_f32_32x32x16_bf16 v[66:81], v[214:217], v[122:125], v[66:81]
	ds_read_b128 v[210:213], v195 offset:63488
	ds_read_b128 v[214:217], v195 offset:64512
	v_add_f32_e32 v193, v147, v146
	v_add_f32_e32 v193, v148, v193
	v_add_f32_e32 v193, v159, v193
	v_add_f32_e32 v193, v160, v193
	v_add_f32_e32 v193, v209, v193
	v_add_f32_e32 v193, v149, v193
	v_add_f32_e32 v193, v161, v193
	v_add_f32_e32 v193, v151, v193
	v_add_f32_e32 v193, v153, v193
	v_add_f32_e32 v193, v154, v193
	v_add_f32_e32 v193, v157, v193
	v_add_f32_e32 v193, v152, v193
	v_add_f32_e32 v193, v155, v193
	v_add_f32_e32 v193, v156, v193
	v_add_f32_e32 v193, v158, v193
	v_add_f32_e32 v193, v144, v193
	v_add_f32_e32 v193, v145, v193
	v_add_f32_e32 v193, v142, v193
	v_add_f32_e32 v193, v143, v193
	v_add_f32_e32 v193, v140, v193
	v_add_f32_e32 v193, v141, v193
	v_add_f32_e32 v193, v138, v193
	v_add_f32_e32 v193, v139, v193
	v_add_f32_e32 v193, v136, v193
	v_add_f32_e32 v193, v137, v193
	s_waitcnt lgkmcnt(1)
	v_mfma_f32_32x32x16_bf16 v[82:97], v[210:213], v[126:129], v[82:97]
	v_add_f32_e32 v193, v134, v193
	v_add_f32_e32 v193, v135, v193
	v_add_f32_e32 v193, v132, v193
	v_add_f32_e32 v193, v133, v193
	v_add_f32_e32 v193, v130, v193
	v_add_f32_e32 v193, v131, v193
	v_mov_b32_e32 v195, v193
	s_waitcnt lgkmcnt(0)
	v_mfma_f32_32x32x16_bf16 v[66:81], v[214:217], v[126:129], v[66:81]
	s_setprio 0
	v_cvt_pk_bf16_f32 v146, v146, v147
	v_cvt_pk_bf16_f32 v147, v148, v159
	v_cvt_pk_bf16_f32 v148, v160, v209
	v_permlane32_swap_b32_e32 v193, v195
	v_cvt_pk_bf16_f32 v149, v149, v161
	v_permlane32_swap_b32_e32 v146, v148
	v_cvt_pk_bf16_f32 v210, v151, v153
	v_cvt_pk_bf16_f32 v211, v154, v157
	v_cvt_pk_bf16_f32 v212, v152, v155
	v_cvt_pk_bf16_f32 v213, v156, v158
	v_cvt_pk_bf16_f32 v152, v144, v145
	v_cvt_pk_bf16_f32 v153, v142, v143
	v_cvt_pk_bf16_f32 v154, v140, v141
	v_cvt_pk_bf16_f32 v155, v138, v139
	v_cvt_pk_bf16_f32 v156, v136, v137
	v_cvt_pk_bf16_f32 v157, v134, v135
	v_cvt_pk_bf16_f32 v158, v132, v133
	v_cvt_pk_bf16_f32 v159, v130, v131
	v_permlane32_swap_b32_e32 v147, v149
	v_permlane32_swap_b32_e32 v210, v212
	v_permlane32_swap_b32_e32 v211, v213
	v_permlane32_swap_b32_e32 v152, v154
	v_permlane32_swap_b32_e32 v153, v155
	v_permlane32_swap_b32_e32 v156, v158
	v_permlane32_swap_b32_e32 v157, v159
	s_lshl_b32 s8, s28, 14
	v_add_u32_e32 v151, s8, v178
	ds_read_b64_tr_b16 v[214:215], v151 offset:0
	ds_read_b64_tr_b16 v[216:217], v151 offset:0x800
	ds_read_b64_tr_b16 v[218:219], v151 offset:0x1000
	ds_read_b64_tr_b16 v[220:221], v151 offset:0x1800
	ds_read_b64_tr_b16 v[222:223], v151 offset:0x2000
	ds_read_b64_tr_b16 v[224:225], v151 offset:0x2800
	ds_read_b64_tr_b16 v[226:227], v151 offset:0x3000
	ds_read_b64_tr_b16 v[228:229], v151 offset:0x3800
	s_cmpk_lg_i32 s4, 0xfd
	s_cselect_b64 s[0:1], -1, 0
	s_cmpk_eq_i32 s4, 0xfd
	s_cselect_b64 s[40:41], -1, 0
	s_and_b64 s[10:11], s[40:41], exec
	s_cselect_b32 s11, s44, s91
	s_cselect_b32 s10, s31, s90
	s_lshl_b64 s[10:11], s[10:11], 9
	s_add_i32 s19, s9, 0x4000
	s_cmp_lg_u32 s6, 2
	s_cselect_b32 s19, s19, 0
	s_add_i32 s19, s19, s18
	s_add_u32 s16, s12, s10
	s_addc_u32 s17, s13, s11
	s_mov_b32 m0, s19
	s_nop 0
	global_load_lds_dwordx4 v187, s[16:17]
	s_add_i32 m0, s19, 0x380
	s_nop 0
	global_load_lds_dwordx4 v187, s[16:17] offset:128
	s_add_u32 s16, s14, s10
	s_addc_u32 s17, s15, s11
	s_add_i32 m0, s19, 0xc000
	s_nop 0
	global_load_lds_dwordx4 v188, s[16:17]
	s_add_u32 s16, s16, 0x4000
	s_addc_u32 s17, s17, 0
	s_add_i32 m0, s19, 0xc400
	s_nop 0
	global_load_lds_dwordx4 v188, s[16:17]
	s_waitcnt lgkmcnt(6)
; #define SBAR() __builtin_amdgcn_sched_barrier(0)
; template <int D0> __device__ __forceinline__ void pv_one(f32x16& od, int vb, bf16x8 pa0, bf16x8 pa1, bf16x8 pa2, bf16x8 pa3) {
;   const s16x4 l0 = tr_read<v_rd_off(D0, 0, 0)>(vb), h0 = tr_read<v_rd_off(D0, 0, 1)>(vb), l1 = tr_read<v_rd_off(D0, 1, 0)>(vb), h1 = tr_read<v_rd_off(D0, 1, 1)>(vb);
;   const s16x4 l2 = tr_read<v_rd_off(D0, 2, 0)>(vb), h2 = tr_read<v_rd_off(D0, 2, 1)>(vb), l3 = tr_read<v_rd_off(D0, 3, 0)>(vb), h3 = tr_read<v_rd_off(D0, 3, 1)>(vb);
;   asm volatile("s_waitcnt lgkmcnt(0)" ::: "memory"); SBAR();
;     ...
;   od = __builtin_amdgcn_mfma_f32_32x32x16_bf16(pa0, PK(l0, h0), od, 0, 0, 0);
;   od = __builtin_amdgcn_mfma_f32_32x32x16_bf16(pa1, PK(l1, h1), od, 0, 0, 0);
;   od = __builtin_amdgcn_mfma_f32_32x32x16_bf16(pa2, PK(l2, h2), od, 0, 0, 0);
;   od = __builtin_amdgcn_mfma_f32_32x32x16_bf16(pa3, PK(l3, h3), od, 0, 0, 0);
;     ...
; }
; __device__ __forceinline__ void pv_d0(f32x16* o, int vb, bf16x8 pa0, bf16x8 pa1, bf16x8 pa2, bf16x8 pa3) {
;   pv_one<0>(o[0], vb, pa0, pa1, pa2, pa3); pv_one<1>(o[1], vb, pa0, pa1, pa2, pa3); pv_one<2>(o[2], vb, pa0, pa1, pa2, pa3); pv_one<3>(o[3], vb, pa0, pa1, pa2, pa3);
; }
	s_nop 0
	s_setprio 1
	v_mfma_f32_32x32x16_bf16 v[2:17], v[146:149], v[214:217], v[2:17]
	ds_read_b64_tr_b16 v[214:215], v151 offset:0x200
	ds_read_b64_tr_b16 v[216:217], v151 offset:0xa00
	s_waitcnt lgkmcnt(6)
	v_mfma_f32_32x32x16_bf16 v[2:17], v[210:213], v[218:221], v[2:17]
	ds_read_b64_tr_b16 v[218:219], v151 offset:0x1200
	ds_read_b64_tr_b16 v[220:221], v151 offset:0x1a00
	s_waitcnt lgkmcnt(6)
	v_mfma_f32_32x32x16_bf16 v[2:17], v[152:155], v[222:225], v[2:17]
	ds_read_b64_tr_b16 v[222:223], v151 offset:0x2200
	ds_read_b64_tr_b16 v[224:225], v151 offset:0x2a00
	s_waitcnt lgkmcnt(6)
	v_mfma_f32_32x32x16_bf16 v[2:17], v[156:159], v[226:229], v[2:17]
	ds_read_b64_tr_b16 v[226:227], v151 offset:0x3200
	ds_read_b64_tr_b16 v[228:229], v151 offset:0x3a00
	s_waitcnt lgkmcnt(6)
	v_mfma_f32_32x32x16_bf16 v[50:65], v[146:149], v[214:217], v[50:65]
	ds_read_b64_tr_b16 v[214:215], v151 offset:0x400
	ds_read_b64_tr_b16 v[216:217], v151 offset:0xc00
	s_waitcnt lgkmcnt(6)
	v_mfma_f32_32x32x16_bf16 v[50:65], v[210:213], v[218:221], v[50:65]
	ds_read_b64_tr_b16 v[218:219], v151 offset:0x1400
	ds_read_b64_tr_b16 v[220:221], v151 offset:0x1c00
	s_waitcnt lgkmcnt(6)
	v_mfma_f32_32x32x16_bf16 v[50:65], v[152:155], v[222:225], v[50:65]
	ds_read_b64_tr_b16 v[222:223], v151 offset:0x2400
	ds_read_b64_tr_b16 v[224:225], v151 offset:0x2c00
	s_waitcnt lgkmcnt(6)
	v_mfma_f32_32x32x16_bf16 v[50:65], v[156:159], v[226:229], v[50:65]
	ds_read_b64_tr_b16 v[226:227], v151 offset:0x3400
	ds_read_b64_tr_b16 v[228:229], v151 offset:0x3c00
	s_waitcnt lgkmcnt(6)
	v_mfma_f32_32x32x16_bf16 v[34:49], v[146:149], v[214:217], v[34:49]
	ds_read_b64_tr_b16 v[214:215], v151 offset:0x600
	ds_read_b64_tr_b16 v[216:217], v151 offset:0xe00
	s_waitcnt lgkmcnt(6)
	v_mfma_f32_32x32x16_bf16 v[34:49], v[210:213], v[218:221], v[34:49]
	ds_read_b64_tr_b16 v[218:219], v151 offset:0x1600
	ds_read_b64_tr_b16 v[220:221], v151 offset:0x1e00
	s_waitcnt lgkmcnt(6)
	v_mfma_f32_32x32x16_bf16 v[34:49], v[152:155], v[222:225], v[34:49]
	ds_read_b64_tr_b16 v[222:223], v151 offset:0x2600
	ds_read_b64_tr_b16 v[224:225], v151 offset:0x2e00
	s_waitcnt lgkmcnt(6)
	v_mfma_f32_32x32x16_bf16 v[34:49], v[156:159], v[226:229], v[34:49]
	ds_read_b64_tr_b16 v[226:227], v151 offset:0x3600
	ds_read_b64_tr_b16 v[228:229], v151 offset:0x3e00
	s_waitcnt lgkmcnt(6)
	v_mfma_f32_32x32x16_bf16 v[18:33], v[146:149], v[214:217], v[18:33]
	v_max_f32_e32 v146, v82, v83
	v_max3_f32 v146, v146, v84, v85
	v_max3_f32 v146, v146, v86, v87
	v_max3_f32 v146, v146, v88, v89
	v_max3_f32 v146, v146, v90, v91
	v_max3_f32 v146, v146, v92, v93
	v_max3_f32 v146, v146, v94, v95
	v_max3_f32 v146, v146, v96, v97
	v_max3_f32 v146, v146, v66, v67
	s_waitcnt lgkmcnt(4)
	v_mfma_f32_32x32x16_bf16 v[18:33], v[210:213], v[218:221], v[18:33]
	v_max3_f32 v146, v146, v68, v69
	v_max3_f32 v146, v146, v70, v71
	v_max3_f32 v146, v146, v72, v73
	v_max3_f32 v146, v146, v74, v75
	v_max3_f32 v146, v146, v76, v77
	v_max3_f32 v146, v146, v78, v79
	v_max3_f32 v146, v146, v80, v81
	v_mov_b32_e32 v147, v146
	s_waitcnt lgkmcnt(2)
	v_mfma_f32_32x32x16_bf16 v[18:33], v[152:155], v[222:225], v[18:33]
	s_nop 0
	v_permlane32_swap_b32_e32 v146, v147
	v_max_f32_e32 v146, v146, v147
	v_sub_f32_e32 v147, v146, v150
	v_cmp_ge_f32_e32 vcc, s25, v147
	v_max_f32_e32 v146, v150, v146
	v_sub_f32_e32 v147, v150, v146
	s_cmp_eq_u64 vcc, exec
	v_mul_f32_e32 v147, 0x3e0293ee, v147
	s_waitcnt lgkmcnt(0)
	v_mfma_f32_32x32x16_bf16 v[18:33], v[156:159], v[226:229], v[18:33]
	s_setprio 0
	s_cselect_b64 s[42:43], -1, 0
	v_exp_f32_e32 v147, v147
	s_add_i32 s7, s9, 0x4000
	s_cmp_lg_u32 s6, 2
	s_cselect_b32 s6, s7, 0
	s_add_i32 s10, s6, 0
	v_cndmask_b32_e64 v196, v147, 1.0, s[42:43]
	v_cmp_gt_f32_e32 vcc, 1.0, v196
	s_cbranch_vccz .LBB0_264
	s_and_saveexec_b64 s[6:7], s[38:39]
	ds_write_b32 v190, v196 offset:128
	s_or_b64 exec, exec, s[6:7]
	s_waitcnt lgkmcnt(0)
	v_add_u32_e32 v147, v173, v181
	ds_read_b128 v[152:155], v147 offset:224
	ds_read_b128 v[156:159], v147 offset:192
	ds_read_b128 v[210:213], v147 offset:160
	ds_read_b128 v[214:217], v147 offset:128
	s_waitcnt lgkmcnt(3)
	v_pk_mul_f32 v[14:15], v[14:15], v[152:153]
	s_waitcnt lgkmcnt(2)
	v_pk_mul_f32 v[10:11], v[10:11], v[156:157]
	s_waitcnt lgkmcnt(1)
	v_pk_mul_f32 v[6:7], v[6:7], v[210:211]
	v_pk_mul_f32 v[16:17], v[16:17], v[154:155]
	v_pk_mul_f32 v[12:13], v[12:13], v[158:159]
	v_pk_mul_f32 v[8:9], v[8:9], v[212:213]
	s_waitcnt lgkmcnt(0)
	v_pk_mul_f32 v[4:5], v[4:5], v[216:217]
	v_pk_mul_f32 v[2:3], v[2:3], v[214:215]
	v_pk_mul_f32 v[62:63], v[62:63], v[152:153]
	v_pk_mul_f32 v[58:59], v[58:59], v[156:157]
	v_pk_mul_f32 v[54:55], v[54:55], v[210:211]
	v_pk_mul_f32 v[64:65], v[64:65], v[154:155]
	v_pk_mul_f32 v[60:61], v[60:61], v[158:159]
	v_pk_mul_f32 v[56:57], v[56:57], v[212:213]
	v_pk_mul_f32 v[52:53], v[52:53], v[216:217]
	v_pk_mul_f32 v[50:51], v[50:51], v[214:215]
	v_pk_mul_f32 v[46:47], v[46:47], v[152:153]
	v_pk_mul_f32 v[42:43], v[42:43], v[156:157]
	v_pk_mul_f32 v[38:39], v[38:39], v[210:211]
	v_pk_mul_f32 v[48:49], v[48:49], v[154:155]
	v_pk_mul_f32 v[44:45], v[44:45], v[158:159]
	v_pk_mul_f32 v[40:41], v[40:41], v[212:213]
	v_pk_mul_f32 v[36:37], v[36:37], v[216:217]
	v_pk_mul_f32 v[34:35], v[34:35], v[214:215]
	v_pk_mul_f32 v[30:31], v[30:31], v[152:153]
	v_pk_mul_f32 v[26:27], v[26:27], v[156:157]
	v_pk_mul_f32 v[22:23], v[22:23], v[210:211]
	v_pk_mul_f32 v[32:33], v[32:33], v[154:155]
	v_pk_mul_f32 v[28:29], v[28:29], v[158:159]
	v_pk_mul_f32 v[24:25], v[24:25], v[212:213]
	v_pk_mul_f32 v[20:21], v[20:21], v[216:217]
	v_pk_mul_f32 v[18:19], v[18:19], v[214:215]
